# v122 + FFN-up silu epilogue packed mul/add
# speedup vs baseline: 1.0011x; 1.0011x over previous
.LBB0_366:
	s_or_b64 exec, exec, s[2:3]
	s_mov_b64 s[6:7], 0xe800000
	s_mov_b64 s[8:9], 0x6100000
	s_mov_b64 s[4:5], 0xf000000
	s_mov_b32 s10, 17
	s_mov_b32 s0, 20
	s_waitcnt lgkmcnt(0)
	s_barrier
	s_mov_b32 s100, 0xbfb8aa3b
	s_mov_b32 s101, 0xbfb8aa3b
	s_getreg_b32 s1, hwreg(HW_REG_HW_ID, 0, 6)
	s_and_b32 s1, s1, 63
	s_lshl_b32 s1, s1, 2
	s_add_i32 s1, s1, 0
	s_add_i32 s1, s1, 0x22ef0
	v_mov_b32_e32 v0, s1
	ds_read_b32 v0, v0
	v_readlane_b32 s12, v253, 10
	v_readlane_b32 s13, v253, 11
	s_movk_i32 s18, 0x1fff
	s_movk_i32 s2, 0x100
	s_waitcnt lgkmcnt(0)
	v_readfirstlane_b32 s1, v0
	v_mov_b32_e32 v0, v177
	s_and_b64 vcc, exec, s[12:13]
	v_mbcnt_lo_u32_b32 v0, -1, v0
	v_mbcnt_hi_u32_b32 v0, -1, v0
	v_lshl_add_u32 v12, s1, 6, v0
	s_nop 0
	v_readfirstlane_b32 s20, v12
	s_cbranch_vccz .LBB0_458
	v_lshlrev_b32_e32 v0, 4, v12
	v_add_u32_e32 v1, 0x2000, v0
	v_ashrrev_i32_e32 v2, 31, v1
	v_lshrrev_b32_e32 v2, 22, v2
	v_add_u32_e32 v2, v1, v2
	v_ashrrev_i32_e32 v13, 10, v2
	v_mul_i32_i24_e32 v3, 0x400, v13
	v_sub_u32_e32 v1, v1, v3
	v_lshrrev_b32_e32 v3, 4, v1
	v_bitop3_b32 v1, v3, v1, 32 bitop3:0x6c
	v_ashrrev_i32_e32 v3, 31, v1
	v_lshrrev_b32_e32 v3, 26, v3
	v_add_u32_e32 v3, v1, v3
	v_ashrrev_i32_e32 v14, 6, v3
	v_and_b32_e32 v3, 0xc0, v3
	v_sub_u32_e32 v1, v1, v3
	v_mov_b32_e32 v4, 1
	v_lshlrev_b32_e32 v2, 5, v13
	v_ashrrev_i16_sdwa v1, v4, sext(v1) dst_sel:DWORD dst_unused:UNUSED_PAD src0_sel:DWORD src1_sel:BYTE_0
	v_and_b32_e32 v2, 32, v2
	v_bfe_i32 v15, v1, 0, 16
	v_add_u32_e32 v1, v2, v15
	v_lshlrev_b32_e32 v2, 3, v13
	v_and_b32_e32 v2, -16, v2
	v_add_u32_e32 v2, v14, v2
	v_mul_lo_u32 v3, v2, s2
	v_lshlrev_b32_e32 v2, 9, v2
	v_lshl_add_u32 v146, v1, 1, v2
	v_bfe_i32 v2, v12, 27, 1
	s_add_u32 s30, s66, s6
	v_lshrrev_b32_e32 v2, 22, v2
	s_addc_u32 s31, s67, s7
	v_add_u32_e32 v2, v0, v2
	s_add_u32 s33, s66, s8
	v_and_b32_e32 v2, 0xfffffc00, v2
	s_addc_u32 s34, s67, s9
	s_ashr_i32 s11, s10, 31
	v_sub_u32_e32 v0, v0, v2
	s_lshl_b64 s[6:7], s[10:11], 3
	v_readlane_b32 s10, v253, 1
	v_lshrrev_b32_e32 v2, 4, v0
	v_readlane_b32 s11, v253, 2
	s_add_u32 s6, s10, s6
	v_bitop3_b32 v2, v2, v0, 32 bitop3:0x6c
	v_ashrrev_i32_e32 v0, 31, v0
	s_addc_u32 s7, s11, s7
	s_ashr_i32 s1, s0, 31
	v_lshrrev_b32_e32 v0, 26, v0
	s_lshl_b64 s[0:1], s[0:1], 3
	v_add_lshl_u32 v144, v1, v3, 1
	v_ashrrev_i32_e32 v1, 31, v12
	v_add_u32_e32 v0, v2, v0
	s_add_u32 s0, s10, s0
	v_lshrrev_b32_e32 v1, 26, v1
	v_ashrrev_i32_e32 v17, 6, v0
	s_addc_u32 s1, s11, s1
	s_ashr_i32 s3, s2, 31
	v_add_u32_e32 v1, v12, v1
	v_mul_i32_i24_e32 v0, 64, v17
	v_readlane_b32 s16, v253, 59
	s_lshl_b64 s[14:15], s[2:3], 9
	v_ashrrev_i32_e32 v16, 6, v1
	v_sub_u32_e32 v0, v2, v0
	v_readlane_b32 s17, v253, 60
	s_load_dwordx2 s[8:9], s[6:7], 0x0
	s_load_dwordx2 s[10:11], s[0:1], 0x0
	v_lshlrev_b32_e32 v1, 5, v16
	v_ashrrev_i16_sdwa v0, v4, sext(v0) dst_sel:DWORD dst_unused:UNUSED_PAD src0_sel:DWORD src1_sel:BYTE_0
	s_mul_i32 s0, s14, s17
	s_mul_hi_u32 s1, s14, s16
	v_and_b32_e32 v1, 32, v1
	v_bfe_i32 v18, v0, 0, 16
	s_add_i32 s6, s1, s0
	s_lshr_b64 s[0:1], s[2:3], 23
	s_ashr_i32 s19, s20, 6
	v_add_u32_e32 v0, v1, v18
	v_lshlrev_b32_e32 v1, 3, v16
	s_mul_i32 s0, s0, s16
	s_ashr_i32 s18, s20, 8
	s_lshl_b64 s[12:13], s[2:3], 8
	s_lshl_b32 s35, s19, 10
	v_and_b32_e32 v1, -16, v1
	s_add_i32 s6, s6, s0
	s_mul_i32 s0, s14, s16
	v_add_u32_e32 v1, v17, v1
	s_add_u32 s0, s33, s0
	v_mul_lo_u32 v2, v1, s2
	s_addc_u32 s1, s34, s6
	s_add_i32 s36, s35, 0
	v_add_lshl_u32 v148, v0, v2, 1
	s_add_i32 m0, s36, 0x10000
	v_mov_b32_e32 v149, v177
	global_load_lds_dwordx4 v148, s[0:1]
	s_add_i32 m0, s36, 0x12000
	s_add_u32 s6, s0, s12
	global_load_lds_dwordx4 v144, s[0:1]
	s_addc_u32 s7, s1, s13
	s_add_i32 m0, s36, 0x14000
	v_mov_b32_e32 v145, v177
	global_load_lds_dwordx4 v148, s[6:7]
	s_add_i32 m0, s36, 0x16000
	v_lshl_add_u64 v[4:5], s[6:7], 0, v[148:149]
	v_lshl_add_u64 v[6:7], s[6:7], 0, v[144:145]
	global_load_lds_dwordx4 v144, s[6:7]
	v_readlane_b32 s6, v254, 9
	v_readlane_b32 s7, v254, 10
	s_add_u32 s6, s30, s6
	v_lshlrev_b32_e32 v1, 9, v1
	s_addc_u32 s7, s31, s7
	s_add_i32 s37, s36, 0x2000
	v_lshl_add_u32 v150, v0, 1, v1
	s_mov_b32 m0, s36
	s_add_u32 s16, s6, 0x10000
	global_load_lds_dwordx4 v150, s[6:7]
	s_mov_b32 m0, s37
	s_addc_u32 s17, s7, 0
	s_add_i32 s40, s36, 0x4000
	global_load_lds_dwordx4 v146, s[6:7]
	s_mov_b32 m0, s40
	s_add_i32 s41, s36, 0x6000
	global_load_lds_dwordx4 v150, s[16:17]
	s_mov_b32 m0, s41
	v_mov_b32_e32 v151, v177
	global_load_lds_dwordx4 v146, s[16:17]
	v_mov_b32_e32 v147, v177
	s_cmp_eq_u32 s18, 1
	v_lshl_add_u64 v[0:1], s[0:1], 0, v[148:149]
	v_lshl_add_u64 v[2:3], s[0:1], 0, v[144:145]
	v_lshl_add_u64 v[8:9], s[6:7], 0, v[150:151]
	v_lshl_add_u64 v[10:11], s[6:7], 0, v[146:147]
	s_cselect_b64 s[16:17], -1, 0
	s_cmp_lg_u32 s18, 1
	s_cbranch_scc1 .LBB0_369
	s_barrier
